# second residual loop: the 12 second-half parameter loads are issued ahead of the first-half stores, one wait instead of eight behind fresh store acks
# speedup vs baseline: 1.0065x; 1.0011x over previous
.LBB0_912:
	s_ashr_i32 s98, s2, 11
	s_mul_i32 s98, s98, 9
	s_ashr_i32 s99, s98, 31
	s_lshl_b64 s[98:99], s[98:99], 12
	s_add_u32 s98, s14, s98
	s_addc_u32 s99, s15, s99
	s_add_u32 s98, s98, 0x5000
	s_addc_u32 s99, s99, 0
	s_add_u32 s100, s98, 0x2000
	s_addc_u32 s101, s99, 0
	s_and_b32 s0, s18, 0x8000
	s_and_b32 s1, s7, 0xfffff000
	s_add_i32 s0, s0, s1
	s_and_b32 s1, s4, 0xffc
	s_or_b32 s0, s0, s1
	s_ashr_i32 s1, s0, 31
	s_lshl_b64 s[0:1], s[0:1], 11
	s_ashr_i32 s5, s4, 31
	v_lshl_add_u64 v[64:65], v[4:5], 0, s[0:1]
	s_lshl_b64 s[10:11], s[4:5], 11
	v_lshl_add_u64 v[0:1], v[6:7], 0, s[10:11]
	global_load_dwordx2 v[80:81], v[64:65], off
	global_load_dwordx2 v[2:3], v[0:1], off
	s_add_i32 s0, s4, 1
	s_ashr_i32 s1, s0, 31
	s_lshl_b64 s[0:1], s[0:1], 11
	v_lshl_add_u64 v[40:41], v[6:7], 0, s[0:1]
	s_add_i32 s0, s4, 2
	s_ashr_i32 s1, s0, 31
	s_lshl_b64 s[0:1], s[0:1], 11
	v_lshl_add_u64 v[88:89], v[6:7], 0, s[0:1]
	s_movk_i32 s0, 0x1000
	v_add_co_u32_e32 v90, vcc, s0, v64
	s_add_i32 s0, s4, 3
	s_nop 0
	v_addc_co_u32_e32 v91, vcc, 0, v65, vcc
	s_ashr_i32 s1, s0, 31
	s_lshl_b64 s[0:1], s[0:1], 11
	v_lshl_add_u64 v[106:107], v[6:7], 0, s[0:1]
	s_mov_b32 s17, s11
	global_load_dwordx2 v[82:83], v[64:65], off offset:512
	global_load_dwordx2 v[202:203], v[0:1], off offset:512
	global_load_dwordx2 v[84:85], v[64:65], off offset:1024
	global_load_dwordx2 v[204:205], v[0:1], off offset:1024
	global_load_dwordx2 v[86:87], v[64:65], off offset:1536
	global_load_dwordx2 v[32:33], v[0:1], off offset:1536
	global_load_dwordx2 v[96:97], v[64:65], off offset:2048
	global_load_dwordx2 v[44:45], v[40:41], off
	global_load_dwordx2 v[126:127], v[64:65], off offset:2560
	global_load_dwordx2 v[206:207], v[40:41], off offset:512
	global_load_dwordx2 v[128:129], v[64:65], off offset:3072
	global_load_dwordx2 v[220:221], v[40:41], off offset:1024
	global_load_dwordx2 v[140:141], v[64:65], off offset:3584
	global_load_dwordx2 v[46:47], v[40:41], off offset:1536
	global_load_dwordx2 v[98:99], v[90:91], off
	global_load_dwordx2 v[64:65], v[88:89], off
	global_load_dwordx2 v[100:101], v[90:91], off offset:512
	global_load_dwordx2 v[222:223], v[88:89], off offset:512
	global_load_dwordx2 v[142:143], v[90:91], off offset:1024
	global_load_dwordx2 v[224:225], v[88:89], off offset:1024
	global_load_dwordx2 v[148:149], v[90:91], off offset:1536
	global_load_dwordx2 v[76:77], v[88:89], off offset:1536
	global_load_dwordx2 v[150:151], v[90:91], off offset:2048
	global_load_dwordx2 v[78:79], v[106:107], off
	global_load_dwordx2 v[152:153], v[90:91], off offset:2560
	global_load_dwordx2 v[92:93], v[106:107], off offset:512
	global_load_dwordx2 v[160:161], v[90:91], off offset:3072
	global_load_dwordx2 v[226:227], v[106:107], off offset:1024
	global_load_dwordx2 v[174:175], v[90:91], off offset:3584
	global_load_dwordx2 v[90:91], v[106:107], off offset:1536
	global_load_dwordx4 v[228:231], v190, s[98:99]
	global_load_dwordx4 v[198:201], v[10:11], off
	global_load_dwordx4 v[232:235], v191, s[98:99]
	global_load_dwordx4 v[236:239], v[12:13], off
	global_load_dwordx4 v[240:243], v192, s[98:99]
	global_load_dwordx4 v[244:247], v[14:15], off
	global_load_dwordx4 v[212:215], v193, s[98:99]
	global_load_dwordx4 v[216:219], v[16:17], off
	s_waitcnt vmcnt(0)
	v_lshlrev_b32_e32 v48, 16, v2
	v_and_b32_e32 v49, 0xffff0000, v2
	v_lshlrev_b32_e32 v50, 16, v3
	v_and_b32_e32 v51, 0xffff0000, v3
	v_lshlrev_b32_e32 v38, 16, v202
	v_and_b32_e32 v39, 0xffff0000, v202
	v_lshlrev_b32_e32 v42, 16, v203
	v_and_b32_e32 v43, 0xffff0000, v203
	v_lshlrev_b32_e32 v132, 16, v84
	v_and_b32_e32 v133, 0xffff0000, v84
	v_lshlrev_b32_e32 v134, 16, v85
	v_lshlrev_b32_e32 v60, 16, v44
	v_and_b32_e32 v61, 0xffff0000, v44
	v_lshlrev_b32_e32 v62, 16, v45
	v_and_b32_e32 v63, 0xffff0000, v45
	v_and_b32_e32 v135, 0xffff0000, v85
	v_lshlrev_b32_e32 v121, 16, v86
	v_and_b32_e32 v119, 0xffff0000, v86
	v_mul_f32_e32 v118, v119, v119
	v_lshlrev_b32_e32 v34, 16, v204
	v_and_b32_e32 v35, 0xffff0000, v204
	v_lshlrev_b32_e32 v36, 16, v205
	v_and_b32_e32 v37, 0xffff0000, v205
	v_lshlrev_b32_e32 v2, 16, v32
	v_and_b32_e32 v3, 0xffff0000, v32
	v_lshlrev_b32_e32 v32, 16, v33
	v_and_b32_e32 v33, 0xffff0000, v33
	v_lshlrev_b32_e32 v56, 16, v206
	v_and_b32_e32 v57, 0xffff0000, v206
	v_lshlrev_b32_e32 v58, 16, v207
	v_and_b32_e32 v59, 0xffff0000, v207
	s_nop 0
	v_lshlrev_b32_e32 v138, 16, v129
	v_and_b32_e32 v139, 0xffff0000, v129
	v_and_b32_e32 v129, 0xffff0000, v140
	v_lshlrev_b32_e32 v72, 16, v64
	v_and_b32_e32 v73, 0xffff0000, v64
	v_lshlrev_b32_e32 v74, 16, v65
	v_and_b32_e32 v75, 0xffff0000, v65
	v_lshlrev_b32_e32 v176, 16, v98
	v_and_b32_e32 v177, 0xffff0000, v98
	v_lshlrev_b32_e32 v98, 16, v99
	v_and_b32_e32 v99, 0xffff0000, v99
	v_lshlrev_b32_e32 v52, 16, v220
	v_and_b32_e32 v53, 0xffff0000, v220
	v_lshlrev_b32_e32 v54, 16, v221
	v_and_b32_e32 v55, 0xffff0000, v221
	v_lshlrev_b32_e32 v44, 16, v46
	v_and_b32_e32 v45, 0xffff0000, v46
	v_lshlrev_b32_e32 v46, 16, v47
	v_and_b32_e32 v47, 0xffff0000, v47
	v_and_b32_e32 v165, 0xffff0000, v101
	v_lshlrev_b32_e32 v66, 16, v222
	v_and_b32_e32 v67, 0xffff0000, v222
	v_lshlrev_b32_e32 v68, 16, v223
	v_and_b32_e32 v69, 0xffff0000, v223
	v_and_b32_e32 v164, 0xffff0000, v100
	v_lshlrev_b32_e32 v163, 16, v101
	v_lshlrev_b32_e32 v162, 16, v100
	v_pk_mul_f32 v[100:101], v[164:165], v[164:165]
	v_lshlrev_b32_e32 v70, 16, v224
	v_pk_fma_f32 v[100:101], v[162:163], v[162:163], v[100:101]
	v_and_b32_e32 v181, 0xffff0000, v151
	v_lshlrev_b32_e32 v122, 16, v92
	v_and_b32_e32 v123, 0xffff0000, v92
	v_lshlrev_b32_e32 v124, 16, v93
	v_and_b32_e32 v125, 0xffff0000, v93
	s_nop 0
	v_pk_add_f32 v[100:101], v[100:101], v[100:101] op_sel:[0,1] op_sel_hi:[1,0]
	v_and_b32_e32 v179, 0xffff0000, v150
	v_lshlrev_b32_e32 v180, 16, v151
	v_and_b32_e32 v173, 0xffff0000, v153
	v_lshlrev_b32_e32 v178, 16, v150
	v_lshlrev_b32_e32 v102, 16, v76
	v_and_b32_e32 v103, 0xffff0000, v76
	v_lshlrev_b32_e32 v104, 16, v77
	v_and_b32_e32 v105, 0xffff0000, v77
	v_lshlrev_b32_e32 v76, 16, v78
	v_and_b32_e32 v77, 0xffff0000, v78
	v_lshlrev_b32_e32 v78, 16, v79
	v_and_b32_e32 v79, 0xffff0000, v79
	v_and_b32_e32 v71, 0xffff0000, v224
	v_lshlrev_b32_e32 v64, 16, v225
	v_and_b32_e32 v65, 0xffff0000, v225
	v_and_b32_e32 v151, 0xffff0000, v174
	v_lshlrev_b32_e32 v114, 16, v227
	v_and_b32_e32 v115, 0xffff0000, v227
	v_and_b32_e32 v93, 0xffff0000, v81
	v_lshlrev_b32_e32 v112, 16, v226
	v_and_b32_e32 v113, 0xffff0000, v226
	v_lshlrev_b32_e32 v108, 16, v90
	v_and_b32_e32 v109, 0xffff0000, v90
	v_lshlrev_b32_e32 v110, 16, v91
	v_and_b32_e32 v111, 0xffff0000, v91
	v_lshlrev_b32_e32 v90, 16, v80
	v_and_b32_e32 v91, 0xffff0000, v80
	v_lshlrev_b32_e32 v92, 16, v81
	v_mul_f32_e32 v80, v93, v93
	v_pk_fma_f32 v[94:95], v[92:93], v[92:93], v[80:81] op_sel_hi:[1,1,0]
	v_lshlrev_b32_e32 v81, 16, v83
	v_lshlrev_b32_e32 v80, 16, v82
	v_and_b32_e32 v83, 0xffff0000, v83
	v_and_b32_e32 v82, 0xffff0000, v82
	v_mul_f32_e32 v84, v91, v91
	v_pk_mul_f32 v[116:117], v[82:83], v[82:83]
	v_pk_fma_f32 v[84:85], v[90:91], v[90:91], v[84:85] op_sel_hi:[1,1,0]
	v_pk_fma_f32 v[130:131], v[80:81], v[80:81], v[116:117]
	v_lshlrev_b32_e32 v116, 16, v87
	v_and_b32_e32 v117, 0xffff0000, v87
	v_mov_b32_e32 v120, v84
	v_mov_b32_e32 v86, v94
	v_mov_b32_e32 v87, v121
	v_pk_add_f32 v[84:85], v[84:85], v[94:95]
	v_pk_mul_f32 v[86:87], v[120:121], v[86:87]
	v_mul_f32_e32 v94, v135, v135
	v_mov_b32_e32 v85, v87
	v_pk_add_f32 v[86:87], v[130:131], v[130:131] op_sel:[0,1] op_sel_hi:[1,0]
	v_mul_f32_e32 v136, v116, v116
	v_mov_b32_e32 v87, v118
	v_pk_add_f32 v[84:85], v[84:85], v[86:87]
	v_mul_f32_e32 v86, v133, v133
	v_mul_f32_e32 v137, v117, v117
	v_pk_fma_f32 v[86:87], v[132:133], v[132:133], v[86:87] op_sel_hi:[1,1,0]
	v_pk_fma_f32 v[94:95], v[134:135], v[134:135], v[94:95] op_sel_hi:[1,1,0]
	v_mov_b32_e32 v87, v136
	v_mov_b32_e32 v95, v137
	v_pk_add_f32 v[86:87], v[86:87], v[94:95]
	v_lshlrev_b32_e32 v94, 16, v96
	v_and_b32_e32 v95, 0xffff0000, v96
	v_lshlrev_b32_e32 v96, 16, v97
	v_and_b32_e32 v97, 0xffff0000, v97
	v_pk_add_f32 v[144:145], v[84:85], v[86:87]
	v_mul_f32_e32 v84, v97, v97
	v_and_b32_e32 v87, 0xffff0000, v127
	v_and_b32_e32 v86, 0xffff0000, v126
	v_pk_fma_f32 v[146:147], v[96:97], v[96:97], v[84:85] op_sel_hi:[1,1,0]
	v_lshlrev_b32_e32 v85, 16, v127
	v_lshlrev_b32_e32 v84, 16, v126
	v_pk_mul_f32 v[126:127], v[86:87], v[86:87]
	v_mul_f32_e32 v118, v95, v95
	v_pk_fma_f32 v[154:155], v[84:85], v[84:85], v[126:127]
	v_lshlrev_b32_e32 v131, 16, v140
	v_lshlrev_b32_e32 v126, 16, v141
	v_and_b32_e32 v127, 0xffff0000, v141
	v_pk_fma_f32 v[140:141], v[94:95], v[94:95], v[118:119] op_sel_hi:[1,1,0]
	v_mov_b32_e32 v156, v146
	v_mov_b32_e32 v130, v140
	v_mov_b32_e32 v157, v131
	v_pk_add_f32 v[140:141], v[140:141], v[146:147]
	v_pk_mul_f32 v[146:147], v[130:131], v[156:157]
	v_and_b32_e32 v137, 0xffff0000, v128
	v_mul_f32_e32 v120, v129, v129
	v_mov_b32_e32 v141, v147
	v_pk_add_f32 v[146:147], v[154:155], v[154:155] op_sel:[0,1] op_sel_hi:[1,0]
	v_lshlrev_b32_e32 v136, 16, v128
	v_mov_b32_e32 v147, v120
	v_mul_f32_e32 v118, v137, v137
	v_pk_add_f32 v[140:141], v[140:141], v[146:147]
	v_pk_fma_f32 v[146:147], v[136:137], v[136:137], v[118:119] op_sel_hi:[1,1,0]
	v_mul_f32_e32 v118, v139, v139
	v_mul_f32_e32 v128, v126, v126
	v_mul_f32_e32 v158, v127, v127
	v_pk_fma_f32 v[154:155], v[138:139], v[138:139], v[118:119] op_sel_hi:[1,1,0]
	v_mov_b32_e32 v147, v128
	v_mov_b32_e32 v155, v158
	v_pk_add_f32 v[146:147], v[146:147], v[154:155]
	v_lshlrev_b32_e32 v154, 16, v142
	v_pk_add_f32 v[140:141], v[140:141], v[146:147]
	v_mov_b32_e32 v147, v144
	v_mov_b32_e32 v146, v140
	v_mov_b32_e32 v144, v141
	v_pk_add_f32 v[140:141], v[146:147], v[144:145]
	v_and_b32_e32 v155, 0xffff0000, v142
	v_lshlrev_b32_e32 v156, 16, v143
	v_and_b32_e32 v157, 0xffff0000, v143
	v_lshlrev_b32_e32 v147, 16, v148
	s_waitcnt lgkmcnt(0)
	v_lshlrev_b32_e32 v142, 16, v149
	v_and_b32_e32 v143, 0xffff0000, v149
	v_mov_b32_e32 v167, v147
	v_mul_f32_e32 v172, v143, v143
	s_waitcnt lgkmcnt(0)
	s_waitcnt lgkmcnt(0)
	s_waitcnt lgkmcnt(0)
	s_waitcnt lgkmcnt(0)
	s_waitcnt lgkmcnt(0)
	s_nop 1
	v_add_f32_dpp v140, v140, v140 row_ror:8 row_mask:0xf bank_mask:0xf
	v_add_f32_dpp v141, v141, v141 row_ror:8 row_mask:0xf bank_mask:0xf
	s_nop 0
	v_add_f32_dpp v140, v140, v140 row_ror:4 row_mask:0xf bank_mask:0xf
	v_add_f32_dpp v141, v141, v141 row_ror:4 row_mask:0xf bank_mask:0xf
	s_nop 0
	v_add_f32_dpp v140, v140, v140 row_ror:2 row_mask:0xf bank_mask:0xf
	v_add_f32_dpp v141, v141, v141 row_ror:2 row_mask:0xf bank_mask:0xf
	s_nop 0
	v_add_f32_dpp v140, v140, v140 row_ror:1 row_mask:0xf bank_mask:0xf
	v_add_f32_dpp v141, v141, v141 row_ror:1 row_mask:0xf bank_mask:0xf
	v_mov_b32_e32 v144, v140
	v_mov_b32_e32 v145, v141
	s_nop 1
	v_permlane16_swap_b32 v140, v144
	v_permlane16_swap_b32 v141, v145
	s_nop 1
	v_add_f32_e32 v140, v140, v144
	v_add_f32_e32 v141, v141, v145
	v_mov_b32_e32 v144, v140
	v_mov_b32_e32 v145, v141
	s_nop 1
	v_permlane32_swap_b32 v140, v144
	v_permlane32_swap_b32 v141, v145
	s_nop 1
	v_pk_add_f32 v[144:145], v[140:141], v[144:145]
	v_mov_b64_e32 v[140:141], s[8:9]
	v_pk_fma_f32 v[144:145], v[144:145], s[6:7], v[140:141] op_sel_hi:[1,0,0]
	s_nop 0
	v_mul_f32_e32 v118, 0x4b800000, v145
	v_cmp_gt_f32_e64 s[0:1], s21, v145
	v_cmp_gt_f32_e32 vcc, s21, v144
	s_nop 0
	v_cndmask_b32_e64 v118, v145, v118, s[0:1]
	v_rsq_f32_e32 v118, v118
	v_and_b32_e32 v145, 0xffff0000, v148
	v_mul_f32_e32 v130, v145, v145
	v_mov_b32_e32 v101, v130
	v_mul_f32_e32 v120, 0x45800000, v118
	v_cndmask_b32_e64 v128, v118, v120, s[0:1]
	v_mul_f32_e32 v118, 0x4b800000, v144
	v_cndmask_b32_e32 v118, v144, v118, vcc
	v_rsq_f32_e32 v118, v118
	v_mul_f32_e32 v144, v142, v142
	v_mul_f32_e32 v130, v151, v151
	v_pk_mul_f32 v[90:91], v[128:129], v[90:91] op_sel_hi:[0,1]
	v_mul_f32_e32 v120, 0x45800000, v118
	v_cndmask_b32_e32 v120, v118, v120, vcc
	v_mul_f32_e32 v118, v99, v99
	v_pk_fma_f32 v[158:159], v[98:99], v[98:99], v[118:119] op_sel_hi:[1,1,0]
	v_mul_f32_e32 v118, v177, v177
	v_pk_fma_f32 v[148:149], v[176:177], v[176:177], v[118:119] op_sel_hi:[1,1,0]
	v_mov_b32_e32 v166, v158
	v_mov_b32_e32 v146, v148
	v_pk_add_f32 v[148:149], v[148:149], v[158:159]
	v_pk_mul_f32 v[158:159], v[146:147], v[166:167]
	v_mul_f32_e32 v118, v155, v155
	v_mov_b32_e32 v149, v159
	v_pk_add_f32 v[100:101], v[148:149], v[100:101]
	v_pk_fma_f32 v[148:149], v[154:155], v[154:155], v[118:119] op_sel_hi:[1,1,0]
	v_mul_f32_e32 v118, v157, v157
	v_pk_fma_f32 v[158:159], v[156:157], v[156:157], v[118:119] op_sel_hi:[1,1,0]
	v_mov_b32_e32 v149, v144
	v_mov_b32_e32 v159, v172
	v_pk_add_f32 v[148:149], v[148:149], v[158:159]
	v_mul_f32_e32 v118, v181, v181
	v_and_b32_e32 v172, 0xffff0000, v152
	v_pk_add_f32 v[100:101], v[100:101], v[148:149]
	v_pk_fma_f32 v[182:183], v[180:181], v[180:181], v[118:119] op_sel_hi:[1,1,0]
	v_lshlrev_b32_e32 v167, 16, v153
	v_lshlrev_b32_e32 v166, 16, v152
	v_pk_mul_f32 v[148:149], v[172:173], v[172:173]
	v_mul_f32_e32 v118, v179, v179
	v_pk_fma_f32 v[194:195], v[166:167], v[166:167], v[148:149]
	v_lshlrev_b32_e32 v153, 16, v174
	v_lshlrev_b32_e32 v148, 16, v175
	v_and_b32_e32 v149, 0xffff0000, v175
	v_pk_fma_f32 v[174:175], v[178:179], v[178:179], v[118:119] op_sel_hi:[1,1,0]
	v_mov_b32_e32 v196, v182
	v_mov_b32_e32 v152, v174
	v_mov_b32_e32 v197, v153
	v_pk_add_f32 v[174:175], v[174:175], v[182:183]
	v_pk_mul_f32 v[182:183], v[152:153], v[196:197]
	v_and_b32_e32 v159, 0xffff0000, v160
	v_mov_b32_e32 v175, v183
	v_pk_add_f32 v[182:183], v[194:195], v[194:195] op_sel:[0,1] op_sel_hi:[1,0]
	v_lshlrev_b32_e32 v158, 16, v160
	v_lshlrev_b32_e32 v160, 16, v161
	v_and_b32_e32 v161, 0xffff0000, v161
	v_mov_b32_e32 v183, v130
	v_mul_f32_e32 v118, v159, v159
	v_pk_add_f32 v[174:175], v[174:175], v[182:183]
	v_pk_fma_f32 v[182:183], v[158:159], v[158:159], v[118:119] op_sel_hi:[1,1,0]
	v_mul_f32_e32 v118, v161, v161
	v_mul_f32_e32 v144, v148, v148
	v_mul_f32_e32 v146, v149, v149
	v_pk_fma_f32 v[194:195], v[160:161], v[160:161], v[118:119] op_sel_hi:[1,1,0]
	v_mov_b32_e32 v183, v144
	v_mov_b32_e32 v195, v146
	v_pk_add_f32 v[182:183], v[182:183], v[194:195]
	v_pk_mul_f32 v[92:93], v[128:129], v[92:93] op_sel_hi:[0,1]
	v_pk_add_f32 v[174:175], v[174:175], v[182:183]
	v_mov_b32_e32 v183, v100
	v_mov_b32_e32 v182, v174
	v_mov_b32_e32 v100, v175
	v_pk_add_f32 v[100:101], v[182:183], v[100:101]
	v_mov_b32_e32 v144, v147
	v_mov_b32_e32 v150, v153
	s_waitcnt lgkmcnt(0)
	s_waitcnt lgkmcnt(0)
	s_waitcnt lgkmcnt(0)
	s_waitcnt lgkmcnt(0)
	s_waitcnt lgkmcnt(0)
	s_waitcnt lgkmcnt(0)
	s_nop 1
	v_add_f32_dpp v100, v100, v100 row_ror:8 row_mask:0xf bank_mask:0xf
	v_add_f32_dpp v101, v101, v101 row_ror:8 row_mask:0xf bank_mask:0xf
	s_nop 0
	v_add_f32_dpp v100, v100, v100 row_ror:4 row_mask:0xf bank_mask:0xf
	v_add_f32_dpp v101, v101, v101 row_ror:4 row_mask:0xf bank_mask:0xf
	s_nop 0
	v_add_f32_dpp v100, v100, v100 row_ror:2 row_mask:0xf bank_mask:0xf
	v_add_f32_dpp v101, v101, v101 row_ror:2 row_mask:0xf bank_mask:0xf
	s_nop 0
	v_add_f32_dpp v100, v100, v100 row_ror:1 row_mask:0xf bank_mask:0xf
	v_add_f32_dpp v101, v101, v101 row_ror:1 row_mask:0xf bank_mask:0xf
	v_mov_b32_e32 v174, v100
	v_mov_b32_e32 v175, v101
	s_nop 1
	v_permlane16_swap_b32 v100, v174
	v_permlane16_swap_b32 v101, v175
	s_nop 1
	v_add_f32_e32 v100, v100, v174
	v_add_f32_e32 v101, v101, v175
	v_mov_b32_e32 v174, v100
	v_mov_b32_e32 v175, v101
	s_nop 1
	v_permlane32_swap_b32 v100, v174
	v_permlane32_swap_b32 v101, v175
	s_nop 1
	v_pk_add_f32 v[100:101], v[100:101], v[174:175]
	s_nop 0
	v_pk_fma_f32 v[100:101], v[100:101], s[6:7], v[140:141] op_sel_hi:[1,0,0]
	s_nop 0
	v_mul_f32_e32 v118, 0x4b800000, v101
	v_cmp_gt_f32_e64 s[0:1], s21, v101
	v_cmp_gt_f32_e32 vcc, s21, v100
	s_nop 0
	v_cndmask_b32_e64 v101, v101, v118, s[0:1]
	v_rsq_f32_e32 v101, v101
	s_nop 0
	v_mul_f32_e32 v118, 0x45800000, v101
	v_cndmask_b32_e64 v146, v101, v118, s[0:1]
	s_ashr_i32 s0, s2, 11
	s_mul_i32 s0, s0, 9
	s_ashr_i32 s1, s0, 31
	s_lshl_b64 s[0:1], s[0:1], 12
	s_add_u32 s5, s14, s0
	s_addc_u32 s13, s15, s1
	s_add_u32 s0, s5, 0x5000
	s_addc_u32 s1, s13, 0
	v_mul_f32_e32 v101, 0x4b800000, v100
	v_cndmask_b32_e32 v100, v100, v101, vcc
	v_rsq_f32_e32 v100, v100
	v_mov_b32_e32 v118, v121
	v_mul_f32_e32 v101, 0x45800000, v100
	v_cndmask_b32_e32 v130, v100, v101, vcc
	v_pk_mul_f32 v[196:197], v[230:231], v[200:201]
	v_pk_mul_f32 v[194:195], v[228:229], v[198:199]
	v_pk_fma_f32 v[174:175], v[92:93], v[196:197], v[50:51]
	v_pk_fma_f32 v[182:183], v[90:91], v[194:195], v[48:49]
	v_cvt_pk_bf16_f32 v49, v174, v175
	v_cvt_pk_bf16_f32 v48, v182, v183
	global_load_dwordx4 v[184:187], v[18:19], off
	global_load_dwordx4 v[202:205], v190, s[100:101]
	global_load_dwordx4 v[206:209], v190, s[100:101] offset:-4096
	global_load_dwordx4 v[220:223], v[20:21], off
	global_load_dwordx4 v[224:227], v191, s[100:101]
	global_load_dwordx4 v[228:231], v191, s[100:101] offset:-4096
	global_store_dwordx2 v[0:1], v[48:49], off
	v_pk_mul_f32 v[48:49], v[174:175], v[174:175]
	v_pk_mul_f32 v[50:51], v[182:183], v[182:183]
	s_nop 0
	v_pk_mov_b32 v[90:91], v[50:51], v[48:49] op_sel:[1,0]
	v_mov_b32_e32 v51, v49
	v_pk_add_f32 v[198:199], v[90:91], v[50:51]
	v_pk_mul_f32 v[48:49], v[120:121], v[94:95] op_sel_hi:[0,1]
	v_pk_mul_f32 v[50:51], v[120:121], v[96:97] op_sel_hi:[0,1]
	v_pk_fma_f32 v[94:95], v[50:51], v[196:197], v[62:63]
	v_pk_fma_f32 v[96:97], v[48:49], v[194:195], v[60:61]
	v_cvt_pk_bf16_f32 v49, v94, v95
	v_cvt_pk_bf16_f32 v48, v96, v97
	global_store_dwordx2 v[40:41], v[48:49], off
	v_pk_mul_f32 v[48:49], v[94:95], v[94:95]
	v_pk_mul_f32 v[50:51], v[96:97], v[96:97]
	s_nop 0
	v_pk_mov_b32 v[60:61], v[50:51], v[48:49] op_sel:[1,0]
	v_mov_b32_e32 v51, v49
	v_pk_add_f32 v[200:201], v[60:61], v[50:51]
	v_pk_mul_f32 v[48:49], v[146:147], v[176:177] op_sel_hi:[0,1]
	v_pk_mul_f32 v[50:51], v[146:147], v[98:99] op_sel_hi:[0,1]
	v_pk_fma_f32 v[98:99], v[196:197], v[50:51], v[74:75]
	v_pk_fma_f32 v[100:101], v[194:195], v[48:49], v[72:73]
	v_cvt_pk_bf16_f32 v49, v98, v99
	v_cvt_pk_bf16_f32 v48, v100, v101
	global_store_dwordx2 v[88:89], v[48:49], off
	v_pk_mul_f32 v[48:49], v[98:99], v[98:99]
	v_pk_mul_f32 v[50:51], v[100:101], v[100:101]
	s_nop 0
	v_pk_mov_b32 v[60:61], v[50:51], v[48:49] op_sel:[1,0]
	v_mov_b32_e32 v51, v49
	v_pk_add_f32 v[176:177], v[60:61], v[50:51]
	v_pk_mul_f32 v[48:49], v[130:131], v[178:179] op_sel_hi:[0,1]
	v_pk_mul_f32 v[50:51], v[130:131], v[180:181] op_sel_hi:[0,1]
	v_pk_fma_f32 v[90:91], v[196:197], v[50:51], v[78:79]
	v_pk_fma_f32 v[92:93], v[194:195], v[48:49], v[76:77]
	v_cvt_pk_bf16_f32 v49, v90, v91
	v_cvt_pk_bf16_f32 v48, v92, v93
	global_store_dwordx2 v[106:107], v[48:49], off
	v_pk_mul_f32 v[48:49], v[90:91], v[90:91]
	v_pk_mul_f32 v[50:51], v[92:93], v[92:93]
	s_nop 0
	v_pk_mov_b32 v[60:61], v[50:51], v[48:49] op_sel:[1,0]
	v_mov_b32_e32 v51, v49
	v_pk_add_f32 v[178:179], v[60:61], v[50:51]
	v_pk_mul_f32 v[48:49], v[232:233], v[236:237]
	v_mov_b32_e32 v60, v80
	v_mov_b32_e32 v61, v82
	v_mov_b32_e32 v82, v81
	v_pk_mul_f32 v[50:51], v[234:235], v[238:239]
	v_pk_mul_f32 v[60:61], v[128:129], v[60:61] op_sel_hi:[0,1]
	v_pk_mul_f32 v[62:63], v[128:129], v[82:83] op_sel_hi:[0,1]
	v_pk_fma_f32 v[76:77], v[62:63], v[50:51], v[42:43]
	v_pk_fma_f32 v[78:79], v[60:61], v[48:49], v[38:39]
	v_cvt_pk_bf16_f32 v39, v76, v77
	v_cvt_pk_bf16_f32 v38, v78, v79
	global_store_dwordx2 v[0:1], v[38:39], off offset:512
	v_pk_mul_f32 v[38:39], v[78:79], v[78:79]
	v_pk_mul_f32 v[42:43], v[76:77], v[76:77]
	s_nop 0
	v_pk_mov_b32 v[60:61], v[38:39], v[42:43] op_sel:[1,0]
	v_mov_b32_e32 v39, v43
	v_mov_b32_e32 v42, v84
	v_mov_b32_e32 v43, v86
	v_mov_b32_e32 v86, v85
	v_pk_add_f32 v[38:39], v[60:61], v[38:39]
	v_pk_mul_f32 v[42:43], v[120:121], v[42:43] op_sel_hi:[0,1]
	v_pk_mul_f32 v[60:61], v[120:121], v[86:87] op_sel_hi:[0,1]
	v_pk_fma_f32 v[80:81], v[60:61], v[50:51], v[58:59]
	v_pk_fma_f32 v[82:83], v[42:43], v[48:49], v[56:57]
	v_cvt_pk_bf16_f32 v43, v80, v81
	v_cvt_pk_bf16_f32 v42, v82, v83
	global_store_dwordx2 v[40:41], v[42:43], off offset:512
	v_pk_mul_f32 v[42:43], v[82:83], v[82:83]
	v_pk_mul_f32 v[56:57], v[80:81], v[80:81]
	s_nop 0
	v_pk_mov_b32 v[58:59], v[42:43], v[56:57] op_sel:[1,0]
	v_mov_b32_e32 v43, v57
	v_mov_b32_e32 v56, v162
	v_mov_b32_e32 v57, v164
	v_mov_b32_e32 v164, v163
	v_pk_add_f32 v[42:43], v[58:59], v[42:43]
	v_pk_mul_f32 v[56:57], v[146:147], v[56:57] op_sel_hi:[0,1]
	v_pk_mul_f32 v[58:59], v[146:147], v[164:165] op_sel_hi:[0,1]
	v_pk_fma_f32 v[84:85], v[58:59], v[50:51], v[68:69]
	v_pk_fma_f32 v[86:87], v[56:57], v[48:49], v[66:67]
	v_cvt_pk_bf16_f32 v57, v84, v85
	v_cvt_pk_bf16_f32 v56, v86, v87
	global_store_dwordx2 v[88:89], v[56:57], off offset:512
	v_pk_mul_f32 v[56:57], v[86:87], v[86:87]
	v_pk_mul_f32 v[58:59], v[84:85], v[84:85]
	s_nop 0
	v_pk_mov_b32 v[60:61], v[56:57], v[58:59] op_sel:[1,0]
	v_mov_b32_e32 v57, v59
	v_pk_add_f32 v[162:163], v[60:61], v[56:57]
	v_mov_b32_e32 v56, v166
	v_mov_b32_e32 v57, v172
	v_mov_b32_e32 v172, v167
	v_pk_mul_f32 v[56:57], v[130:131], v[56:57] op_sel_hi:[0,1]
	v_pk_mul_f32 v[58:59], v[130:131], v[172:173] op_sel_hi:[0,1]
	v_pk_fma_f32 v[72:73], v[50:51], v[58:59], v[124:125]
	v_pk_fma_f32 v[74:75], v[48:49], v[56:57], v[122:123]
	v_cvt_pk_bf16_f32 v49, v72, v73
	v_cvt_pk_bf16_f32 v48, v74, v75
	global_store_dwordx2 v[106:107], v[48:49], off offset:512
	v_pk_mul_f32 v[48:49], v[74:75], v[74:75]
	v_pk_mul_f32 v[50:51], v[72:73], v[72:73]
	s_nop 0
	v_pk_mov_b32 v[56:57], v[48:49], v[50:51] op_sel:[1,0]
	v_mov_b32_e32 v49, v51
	v_pk_add_f32 v[122:123], v[56:57], v[48:49]
	v_pk_mul_f32 v[50:51], v[242:243], v[246:247]
	v_pk_mul_f32 v[48:49], v[240:241], v[244:245]
	v_pk_mul_f32 v[56:57], v[128:129], v[132:133] op_sel_hi:[0,1]
	v_pk_mul_f32 v[58:59], v[128:129], v[134:135] op_sel_hi:[0,1]
	v_pk_fma_f32 v[60:61], v[58:59], v[50:51], v[36:37]
	v_pk_fma_f32 v[66:67], v[56:57], v[48:49], v[34:35]
	v_cvt_pk_bf16_f32 v35, v60, v61
	v_cvt_pk_bf16_f32 v34, v66, v67
	global_store_dwordx2 v[0:1], v[34:35], off offset:1024
	v_pk_mul_f32 v[34:35], v[120:121], v[136:137] op_sel_hi:[0,1]
	v_pk_mul_f32 v[36:37], v[120:121], v[138:139] op_sel_hi:[0,1]
	v_pk_fma_f32 v[62:63], v[36:37], v[50:51], v[54:55]
	v_pk_fma_f32 v[68:69], v[34:35], v[48:49], v[52:53]
	v_cvt_pk_bf16_f32 v35, v62, v63
	v_cvt_pk_bf16_f32 v34, v68, v69
	global_store_dwordx2 v[40:41], v[34:35], off offset:1024
	v_pk_mul_f32 v[34:35], v[146:147], v[154:155] op_sel_hi:[0,1]
	v_pk_mul_f32 v[36:37], v[146:147], v[156:157] op_sel_hi:[0,1]
	v_pk_fma_f32 v[64:65], v[36:37], v[50:51], v[64:65]
	v_pk_fma_f32 v[70:71], v[34:35], v[48:49], v[70:71]
	v_cvt_pk_bf16_f32 v35, v64, v65
	v_cvt_pk_bf16_f32 v34, v70, v71
	global_store_dwordx2 v[88:89], v[34:35], off offset:1024
	v_pk_mul_f32 v[34:35], v[130:131], v[158:159] op_sel_hi:[0,1]
	v_pk_mul_f32 v[36:37], v[130:131], v[160:161] op_sel_hi:[0,1]
	v_pk_fma_f32 v[56:57], v[36:37], v[50:51], v[114:115]
	v_pk_fma_f32 v[58:59], v[34:35], v[48:49], v[112:113]
	v_cvt_pk_bf16_f32 v35, v56, v57
	v_cvt_pk_bf16_f32 v34, v58, v59
	global_store_dwordx2 v[106:107], v[34:35], off offset:1024
	s_nop 0
	v_pk_mul_f32 v[50:51], v[214:215], v[218:219]
	v_pk_mul_f32 v[48:49], v[212:213], v[216:217]
	v_pk_mul_f32 v[34:35], v[128:129], v[118:119] op_sel_hi:[0,1]
	v_pk_mul_f32 v[36:37], v[128:129], v[116:117] op_sel_hi:[0,1]
	v_pk_fma_f32 v[32:33], v[36:37], v[50:51], v[32:33]
	v_pk_fma_f32 v[34:35], v[34:35], v[48:49], v[2:3]
	v_cvt_pk_bf16_f32 v3, v32, v33
	v_cvt_pk_bf16_f32 v2, v34, v35
	global_load_dwordx4 v[232:235], v[24:25], off
	global_load_dwordx4 v[236:239], v192, s[100:101]
	global_load_dwordx4 v[240:243], v192, s[100:101] offset:-4096
	global_load_dwordx4 v[244:247], v[28:29], off
	global_load_dwordx4 v[212:215], v193, s[100:101]
	global_load_dwordx4 v[216:219], v193, s[100:101] offset:-4096
	global_store_dwordx2 v[0:1], v[2:3], off offset:1536
	v_mul_f32_e32 v2, v34, v34
	v_pk_add_f32 v[0:1], v[198:199], v[198:199] op_sel:[0,1] op_sel_hi:[1,0]
	v_mul_f32_e32 v36, v35, v35
	v_mov_b32_e32 v1, v2
	v_pk_add_f32 v[2:3], v[38:39], v[38:39] op_sel:[0,1] op_sel_hi:[1,0]
	v_mul_f32_e32 v37, v32, v32
	v_mov_b32_e32 v3, v36
	v_pk_add_f32 v[0:1], v[0:1], v[2:3]
	v_mul_f32_e32 v2, v67, v67
	v_pk_fma_f32 v[2:3], v[66:67], v[66:67], v[2:3] op_sel_hi:[1,1,0]
	v_mul_f32_e32 v36, v61, v61
	v_mul_f32_e32 v52, v33, v33
	v_mov_b32_e32 v3, v37
	v_pk_fma_f32 v[36:37], v[60:61], v[60:61], v[36:37] op_sel_hi:[1,1,0]
	v_mov_b32_e32 v128, v131
	v_mov_b32_e32 v37, v52
	v_pk_add_f32 v[2:3], v[2:3], v[36:37]
	v_pk_mul_f32 v[36:37], v[120:121], v[126:127] op_sel_hi:[0,1]
	v_pk_add_f32 v[0:1], v[0:1], v[2:3]
	v_pk_mul_f32 v[2:3], v[120:121], v[128:129] op_sel_hi:[0,1]
	v_pk_fma_f32 v[36:37], v[36:37], v[50:51], v[46:47]
	v_pk_fma_f32 v[38:39], v[2:3], v[48:49], v[44:45]
	v_cvt_pk_bf16_f32 v3, v36, v37
	v_cvt_pk_bf16_f32 v2, v38, v39
	global_store_dwordx2 v[40:41], v[2:3], off offset:1536
	v_mul_f32_e32 v40, v38, v38
	v_pk_add_f32 v[2:3], v[200:201], v[200:201] op_sel:[0,1] op_sel_hi:[1,0]
	v_mul_f32_e32 v44, v39, v39
	v_mov_b32_e32 v3, v40
	v_pk_add_f32 v[40:41], v[42:43], v[42:43] op_sel:[0,1] op_sel_hi:[1,0]
	v_mul_f32_e32 v42, v63, v63
	v_mov_b32_e32 v41, v44
	v_pk_add_f32 v[2:3], v[2:3], v[40:41]
	v_mul_f32_e32 v40, v69, v69
	v_mul_f32_e32 v45, v36, v36
	v_mul_f32_e32 v46, v37, v37
	v_pk_fma_f32 v[40:41], v[68:69], v[68:69], v[40:41] op_sel_hi:[1,1,0]
	v_pk_fma_f32 v[42:43], v[62:63], v[62:63], v[42:43] op_sel_hi:[1,1,0]
	v_mov_b32_e32 v41, v45
	v_mov_b32_e32 v43, v46
	v_pk_add_f32 v[40:41], v[40:41], v[42:43]
	v_pk_mul_f32 v[42:43], v[146:147], v[144:145] op_sel_hi:[0,1]
	v_pk_add_f32 v[2:3], v[2:3], v[40:41]
	v_pk_mul_f32 v[40:41], v[146:147], v[142:143] op_sel_hi:[0,1]
	v_pk_fma_f32 v[40:41], v[40:41], v[50:51], v[104:105]
	v_pk_fma_f32 v[42:43], v[42:43], v[48:49], v[102:103]
	v_cvt_pk_bf16_f32 v45, v40, v41
	v_cvt_pk_bf16_f32 v44, v42, v43
	global_store_dwordx2 v[88:89], v[44:45], off offset:1536
	v_mul_f32_e32 v46, v42, v42
	v_pk_add_f32 v[44:45], v[176:177], v[176:177] op_sel:[0,1] op_sel_hi:[1,0]
	v_mul_f32_e32 v52, v43, v43
	v_mov_b32_e32 v45, v46
	v_pk_add_f32 v[46:47], v[162:163], v[162:163] op_sel:[0,1] op_sel_hi:[1,0]
	v_mul_f32_e32 v53, v40, v40
	v_mov_b32_e32 v47, v52
	v_pk_add_f32 v[44:45], v[44:45], v[46:47]
	v_mul_f32_e32 v46, v71, v71
	v_pk_fma_f32 v[46:47], v[70:71], v[70:71], v[46:47] op_sel_hi:[1,1,0]
	v_mul_f32_e32 v52, v65, v65
	v_mul_f32_e32 v54, v41, v41
	v_mov_b32_e32 v47, v53
	v_pk_fma_f32 v[52:53], v[64:65], v[64:65], v[52:53] op_sel_hi:[1,1,0]
	s_nop 0
	v_mov_b32_e32 v53, v54
	v_pk_add_f32 v[46:47], v[46:47], v[52:53]
	s_nop 0
	v_pk_add_f32 v[52:53], v[44:45], v[46:47]
	v_pk_mul_f32 v[46:47], v[130:131], v[150:151] op_sel_hi:[0,1]
	v_pk_mul_f32 v[44:45], v[130:131], v[148:149] op_sel_hi:[0,1]
	v_pk_fma_f32 v[44:45], v[44:45], v[50:51], v[110:111]
	v_pk_fma_f32 v[46:47], v[46:47], v[48:49], v[108:109]
	v_cvt_pk_bf16_f32 v49, v44, v45
	v_cvt_pk_bf16_f32 v48, v46, v47
	global_store_dwordx2 v[106:107], v[48:49], off offset:1536
	v_mul_f32_e32 v50, v46, v46
	v_pk_add_f32 v[48:49], v[178:179], v[178:179] op_sel:[0,1] op_sel_hi:[1,0]
	v_mul_f32_e32 v54, v47, v47
	v_mov_b32_e32 v49, v50
	v_pk_add_f32 v[50:51], v[122:123], v[122:123] op_sel:[0,1] op_sel_hi:[1,0]
	v_mul_f32_e32 v55, v44, v44
	v_mov_b32_e32 v51, v54
	v_pk_add_f32 v[48:49], v[48:49], v[50:51]
	v_mul_f32_e32 v50, v59, v59
	v_pk_fma_f32 v[50:51], v[58:59], v[58:59], v[50:51] op_sel_hi:[1,1,0]
	v_mul_f32_e32 v54, v57, v57
	v_mul_f32_e32 v88, v45, v45
	v_mov_b32_e32 v51, v55
	v_pk_fma_f32 v[54:55], v[56:57], v[56:57], v[54:55] op_sel_hi:[1,1,0]
	s_nop 0
	v_mov_b32_e32 v55, v88
	v_pk_add_f32 v[50:51], v[50:51], v[54:55]
	s_nop 0
	v_pk_add_f32 v[54:55], v[48:49], v[50:51]
	v_mov_b32_e32 v48, v2
	v_mov_b32_e32 v49, v0
	v_mov_b32_e32 v0, v3
	v_pk_add_f32 v[0:1], v[48:49], v[0:1]
	s_waitcnt lgkmcnt(0)
	s_waitcnt lgkmcnt(0)
	s_waitcnt lgkmcnt(0)
	s_waitcnt lgkmcnt(0)
	s_waitcnt lgkmcnt(0)
	s_waitcnt lgkmcnt(0)
	s_nop 1
	v_add_f32_dpp v0, v0, v0 row_ror:8 row_mask:0xf bank_mask:0xf
	v_add_f32_dpp v1, v1, v1 row_ror:8 row_mask:0xf bank_mask:0xf
	s_nop 0
	v_add_f32_dpp v0, v0, v0 row_ror:4 row_mask:0xf bank_mask:0xf
	v_add_f32_dpp v1, v1, v1 row_ror:4 row_mask:0xf bank_mask:0xf
	s_nop 0
	v_add_f32_dpp v0, v0, v0 row_ror:2 row_mask:0xf bank_mask:0xf
	v_add_f32_dpp v1, v1, v1 row_ror:2 row_mask:0xf bank_mask:0xf
	s_nop 0
	v_add_f32_dpp v0, v0, v0 row_ror:1 row_mask:0xf bank_mask:0xf
	v_add_f32_dpp v1, v1, v1 row_ror:1 row_mask:0xf bank_mask:0xf
	v_mov_b32_e32 v2, v0
	v_mov_b32_e32 v3, v1
	s_nop 1
	v_permlane16_swap_b32 v0, v2
	v_permlane16_swap_b32 v1, v3
	s_nop 1
	v_add_f32_e32 v0, v0, v2
	v_add_f32_e32 v1, v1, v3
	v_mov_b32_e32 v2, v0
	v_mov_b32_e32 v3, v1
	s_nop 1
	v_permlane32_swap_b32 v0, v2
	v_permlane32_swap_b32 v1, v3
	s_nop 1
	v_pk_add_f32 v[0:1], v[0:1], v[2:3]
	s_nop 0
	v_pk_fma_f32 v[0:1], v[0:1], s[6:7], v[140:141] op_sel_hi:[1,0,0]
	s_nop 0
	v_mul_f32_e32 v2, 0x4b800000, v1
	v_cmp_gt_f32_e64 s[0:1], s21, v1
	v_cmp_gt_f32_e32 vcc, s21, v0
	s_nop 0
	v_cndmask_b32_e64 v1, v1, v2, s[0:1]
	v_rsq_f32_e32 v1, v1
	s_nop 0
	v_mul_f32_e32 v2, 0x45800000, v1
	v_cndmask_b32_e64 v50, v1, v2, s[0:1]
	v_mul_f32_e32 v1, 0x4b800000, v0
	v_cndmask_b32_e32 v0, v0, v1, vcc
	v_rsq_f32_e32 v0, v0
	v_pk_mul_f32 v[78:79], v[78:79], v[50:51] op_sel_hi:[1,0]
	v_pk_mul_f32 v[76:77], v[76:77], v[50:51] op_sel_hi:[1,0]
	v_pk_mul_f32 v[66:67], v[66:67], v[50:51] op_sel_hi:[1,0]
	v_mul_f32_e32 v1, 0x45800000, v0
	v_cndmask_b32_e32 v48, v0, v1, vcc
	v_mov_b32_e32 v0, v54
	v_mov_b32_e32 v1, v52
	v_mov_b32_e32 v52, v55
	v_pk_add_f32 v[0:1], v[0:1], v[52:53]
	v_pk_mul_f32 v[96:97], v[96:97], v[48:49] op_sel_hi:[1,0]
	v_pk_mul_f32 v[94:95], v[94:95], v[48:49] op_sel_hi:[1,0]
	v_pk_mul_f32 v[60:61], v[60:61], v[50:51] op_sel_hi:[1,0]
	v_pk_mul_f32 v[62:63], v[62:63], v[48:49] op_sel_hi:[1,0]
	s_waitcnt lgkmcnt(0)
	v_pk_mul_f32 v[34:35], v[34:35], v[50:51] op_sel_hi:[1,0]
	v_pk_mul_f32 v[32:33], v[32:33], v[50:51] op_sel_hi:[1,0]
	s_waitcnt lgkmcnt(0)
	s_waitcnt lgkmcnt(0)
	s_waitcnt lgkmcnt(0)
	s_waitcnt lgkmcnt(0)
	s_waitcnt lgkmcnt(0)
	s_nop 1
	v_add_f32_dpp v0, v0, v0 row_ror:8 row_mask:0xf bank_mask:0xf
	v_add_f32_dpp v1, v1, v1 row_ror:8 row_mask:0xf bank_mask:0xf
	s_nop 0
	v_add_f32_dpp v0, v0, v0 row_ror:4 row_mask:0xf bank_mask:0xf
	v_add_f32_dpp v1, v1, v1 row_ror:4 row_mask:0xf bank_mask:0xf
	s_nop 0
	v_add_f32_dpp v0, v0, v0 row_ror:2 row_mask:0xf bank_mask:0xf
	v_add_f32_dpp v1, v1, v1 row_ror:2 row_mask:0xf bank_mask:0xf
	s_nop 0
	v_add_f32_dpp v0, v0, v0 row_ror:1 row_mask:0xf bank_mask:0xf
	v_add_f32_dpp v1, v1, v1 row_ror:1 row_mask:0xf bank_mask:0xf
	v_mov_b32_e32 v2, v0
	v_mov_b32_e32 v3, v1
	s_nop 1
	v_permlane16_swap_b32 v0, v2
	v_permlane16_swap_b32 v1, v3
	s_nop 1
	v_add_f32_e32 v0, v0, v2
	v_add_f32_e32 v1, v1, v3
	v_mov_b32_e32 v2, v0
	v_mov_b32_e32 v3, v1
	s_nop 1
	v_permlane32_swap_b32 v0, v2
	v_permlane32_swap_b32 v1, v3
	s_nop 1
	v_pk_add_f32 v[0:1], v[0:1], v[2:3]
	s_nop 0
	v_pk_fma_f32 v[0:1], v[0:1], s[6:7], v[140:141] op_sel_hi:[1,0,0]
	s_nop 0
	v_mul_f32_e32 v2, 0x4b800000, v1
	v_cmp_gt_f32_e64 s[0:1], s21, v1
	v_cmp_gt_f32_e32 vcc, s21, v0
	s_nop 0
	v_cndmask_b32_e64 v1, v1, v2, s[0:1]
	v_rsq_f32_e32 v1, v1
	s_nop 0
	v_mul_f32_e32 v2, 0x45800000, v1
	v_cndmask_b32_e64 v54, v1, v2, s[0:1]
	v_mul_f32_e32 v1, 0x4b800000, v0
	v_cndmask_b32_e32 v0, v0, v1, vcc
	v_rsq_f32_e32 v0, v0
	s_add_u32 s0, s5, 0x6000
	s_addc_u32 s1, s13, 0
	s_add_u32 s12, s5, 0x7000
	v_mul_f32_e32 v1, 0x45800000, v0
	v_cndmask_b32_e32 v52, v0, v1, vcc
	s_addc_u32 s13, s13, 0
	v_pk_mul_f32 v[92:93], v[92:93], v[52:53] op_sel_hi:[1,0]
	v_pk_mul_f32 v[90:91], v[90:91], v[52:53] op_sel_hi:[1,0]
	s_or_b32 s16, s10, 0x1000
	v_pk_mul_f32 v[74:75], v[74:75], v[52:53] op_sel_hi:[1,0]
	v_pk_mul_f32 v[72:73], v[72:73], v[52:53] op_sel_hi:[1,0]
	v_pk_mul_f32 v[58:59], v[58:59], v[52:53] op_sel_hi:[1,0]
	v_pk_mul_f32 v[56:57], v[56:57], v[52:53] op_sel_hi:[1,0]
	s_add_i32 s2, s2, s3
	s_add_i32 s7, s7, s9
	s_add_i32 s18, s18, s19
	s_add_i32 s4, s4, s20
	s_waitcnt vmcnt(0)
	v_pk_add_f32 v[88:89], v[204:205], 1.0 op_sel_hi:[1,0]
	v_pk_add_f32 v[108:109], v[202:203], 1.0 op_sel_hi:[1,0]
	v_pk_mul_f32 v[102:103], v[186:187], v[88:89]
	v_pk_mul_f32 v[104:105], v[184:185], v[108:109]
	v_pk_mul_f32 v[88:89], v[182:183], v[50:51] op_sel_hi:[1,0]
	v_pk_mul_f32 v[106:107], v[174:175], v[50:51] op_sel_hi:[1,0]
	v_pk_fma_f32 v[88:89], v[88:89], v[104:105], v[206:207]
	v_pk_fma_f32 v[94:95], v[94:95], v[102:103], v[208:209]
	v_pk_fma_f32 v[96:97], v[96:97], v[104:105], v[206:207]
	v_pk_fma_f32 v[108:109], v[106:107], v[102:103], v[208:209]
	v_cvt_pk_bf16_f32 v106, v88, v89
	v_lshl_add_u64 v[88:89], v[8:9], 0, s[10:11]
	v_cvt_pk_bf16_f32 v96, v96, v97
	v_cvt_pk_bf16_f32 v97, v94, v95
	global_store_dwordx2 v[88:89], v[96:97], off offset:2048
	v_pk_mul_f32 v[94:95], v[100:101], v[54:55] op_sel_hi:[1,0]
	v_pk_mul_f32 v[96:97], v[98:99], v[54:55] op_sel_hi:[1,0]
	v_pk_fma_f32 v[94:95], v[104:105], v[94:95], v[206:207]
	v_pk_fma_f32 v[96:97], v[102:103], v[96:97], v[208:209]
	v_pk_fma_f32 v[2:3], v[102:103], v[90:91], v[208:209]
	v_pk_fma_f32 v[0:1], v[104:105], v[92:93], v[206:207]
	s_or_b32 s10, s10, 0x1800
	v_cvt_pk_bf16_f32 v107, v108, v109
	v_cvt_pk_bf16_f32 v94, v94, v95
	v_cvt_pk_bf16_f32 v95, v96, v97
	v_lshl_add_u64 v[96:97], v[8:9], 0, s[16:17]
	v_cvt_pk_bf16_f32 v0, v0, v1
	v_cvt_pk_bf16_f32 v1, v2, v3
	v_lshl_add_u64 v[2:3], v[8:9], 0, s[10:11]
	global_store_dwordx2 v[88:89], v[106:107], off
	global_store_dwordx2 v[96:97], v[94:95], off
	global_store_dwordx2 v[2:3], v[0:1], off
	s_nop 0
	s_cmpk_lt_i32 s2, 0x4000
	v_pk_add_f32 v[92:93], v[226:227], 1.0 op_sel_hi:[1,0]
	v_pk_add_f32 v[90:91], v[224:225], 1.0 op_sel_hi:[1,0]
	v_pk_mul_f32 v[2:3], v[222:223], v[92:93]
	v_pk_mul_f32 v[0:1], v[220:221], v[90:91]
	v_pk_fma_f32 v[76:77], v[76:77], v[2:3], v[230:231]
	v_pk_fma_f32 v[78:79], v[78:79], v[0:1], v[228:229]
	s_nop 0
	v_cvt_pk_bf16_f32 v78, v78, v79
	v_cvt_pk_bf16_f32 v79, v76, v77
	global_store_dwordx2 v[88:89], v[78:79], off offset:512
	v_pk_mul_f32 v[76:77], v[82:83], v[48:49] op_sel_hi:[1,0]
	v_pk_mul_f32 v[78:79], v[80:81], v[48:49] op_sel_hi:[1,0]
	v_pk_fma_f32 v[76:77], v[76:77], v[0:1], v[228:229]
	v_pk_fma_f32 v[78:79], v[78:79], v[2:3], v[230:231]
	v_cvt_pk_bf16_f32 v76, v76, v77
	v_cvt_pk_bf16_f32 v77, v78, v79
	global_store_dwordx2 v[88:89], v[76:77], off offset:2560
	v_pk_mul_f32 v[76:77], v[86:87], v[54:55] op_sel_hi:[1,0]
	v_pk_mul_f32 v[78:79], v[84:85], v[54:55] op_sel_hi:[1,0]
	v_pk_fma_f32 v[76:77], v[76:77], v[0:1], v[228:229]
	v_pk_fma_f32 v[78:79], v[78:79], v[2:3], v[230:231]
	v_pk_fma_f32 v[2:3], v[2:3], v[72:73], v[230:231]
	v_pk_fma_f32 v[0:1], v[0:1], v[74:75], v[228:229]
	v_cvt_pk_bf16_f32 v76, v76, v77
	v_cvt_pk_bf16_f32 v77, v78, v79
	v_lshl_add_u64 v[78:79], v[22:23], 0, s[16:17]
	v_cvt_pk_bf16_f32 v0, v0, v1
	v_cvt_pk_bf16_f32 v1, v2, v3
	v_lshl_add_u64 v[2:3], v[22:23], 0, s[10:11]
	global_store_dwordx2 v[78:79], v[76:77], off
	global_store_dwordx2 v[2:3], v[0:1], off
	s_nop 0
	v_pk_add_f32 v[74:75], v[238:239], 1.0 op_sel_hi:[1,0]
	v_pk_add_f32 v[72:73], v[236:237], 1.0 op_sel_hi:[1,0]
	v_pk_mul_f32 v[2:3], v[234:235], v[74:75]
	v_pk_mul_f32 v[0:1], v[232:233], v[72:73]
	v_pk_fma_f32 v[60:61], v[60:61], v[2:3], v[242:243]
	v_pk_fma_f32 v[66:67], v[66:67], v[0:1], v[240:241]
	v_pk_fma_f32 v[62:63], v[62:63], v[2:3], v[242:243]
	v_cvt_pk_bf16_f32 v66, v66, v67
	v_cvt_pk_bf16_f32 v67, v60, v61
	v_pk_mul_f32 v[60:61], v[68:69], v[48:49] op_sel_hi:[1,0]
	global_store_dwordx2 v[88:89], v[66:67], off offset:1024
	v_pk_fma_f32 v[60:61], v[60:61], v[0:1], v[240:241]
	s_nop 0
	v_cvt_pk_bf16_f32 v60, v60, v61
	v_cvt_pk_bf16_f32 v61, v62, v63
	global_store_dwordx2 v[88:89], v[60:61], off offset:3072
	v_pk_mul_f32 v[60:61], v[70:71], v[54:55] op_sel_hi:[1,0]
	v_pk_mul_f32 v[62:63], v[64:65], v[54:55] op_sel_hi:[1,0]
	v_pk_fma_f32 v[60:61], v[60:61], v[0:1], v[240:241]
	v_pk_fma_f32 v[62:63], v[62:63], v[2:3], v[242:243]
	v_pk_fma_f32 v[2:3], v[56:57], v[2:3], v[242:243]
	v_pk_fma_f32 v[0:1], v[58:59], v[0:1], v[240:241]
	v_cvt_pk_bf16_f32 v60, v60, v61
	v_cvt_pk_bf16_f32 v61, v62, v63
	v_lshl_add_u64 v[62:63], v[26:27], 0, s[16:17]
	v_cvt_pk_bf16_f32 v0, v0, v1
	v_cvt_pk_bf16_f32 v1, v2, v3
	v_lshl_add_u64 v[2:3], v[26:27], 0, s[10:11]
	global_store_dwordx2 v[62:63], v[60:61], off
	global_store_dwordx2 v[2:3], v[0:1], off
	s_nop 0
	v_pk_add_f32 v[58:59], v[214:215], 1.0 op_sel_hi:[1,0]
	v_pk_add_f32 v[56:57], v[212:213], 1.0 op_sel_hi:[1,0]
	v_pk_mul_f32 v[2:3], v[246:247], v[58:59]
	v_pk_mul_f32 v[0:1], v[244:245], v[56:57]
	v_pk_fma_f32 v[32:33], v[32:33], v[2:3], v[218:219]
	v_pk_fma_f32 v[34:35], v[34:35], v[0:1], v[216:217]
	s_nop 0
	v_cvt_pk_bf16_f32 v34, v34, v35
	v_cvt_pk_bf16_f32 v35, v32, v33
	global_store_dwordx2 v[88:89], v[34:35], off offset:1536
	v_pk_mul_f32 v[32:33], v[38:39], v[48:49] op_sel_hi:[1,0]
	v_pk_mul_f32 v[34:35], v[36:37], v[48:49] op_sel_hi:[1,0]
	v_pk_fma_f32 v[32:33], v[32:33], v[0:1], v[216:217]
	v_pk_fma_f32 v[34:35], v[34:35], v[2:3], v[218:219]
	v_cvt_pk_bf16_f32 v32, v32, v33
	v_cvt_pk_bf16_f32 v33, v34, v35
	global_store_dwordx2 v[88:89], v[32:33], off offset:3584
	v_pk_mul_f32 v[32:33], v[42:43], v[54:55] op_sel_hi:[1,0]
	v_pk_mul_f32 v[34:35], v[40:41], v[54:55] op_sel_hi:[1,0]
	v_pk_fma_f32 v[32:33], v[32:33], v[0:1], v[216:217]
	v_pk_fma_f32 v[34:35], v[34:35], v[2:3], v[218:219]
	v_cvt_pk_bf16_f32 v32, v32, v33
	v_cvt_pk_bf16_f32 v33, v34, v35
	v_lshl_add_u64 v[34:35], v[30:31], 0, s[16:17]
	global_store_dwordx2 v[34:35], v[32:33], off
	v_pk_mul_f32 v[32:33], v[46:47], v[52:53] op_sel_hi:[1,0]
	v_pk_mul_f32 v[34:35], v[44:45], v[52:53] op_sel_hi:[1,0]
	v_pk_fma_f32 v[0:1], v[32:33], v[0:1], v[216:217]
	v_pk_fma_f32 v[2:3], v[34:35], v[2:3], v[218:219]
	v_cvt_pk_bf16_f32 v0, v0, v1
	v_cvt_pk_bf16_f32 v1, v2, v3
	v_lshl_add_u64 v[2:3], v[30:31], 0, s[10:11]
	global_store_dwordx2 v[2:3], v[0:1], off
	s_cbranch_scc1 .LBB0_912
